# instruction selection: accumulator zero-init as 64 v_mov_b64 instead of 128 v_mov_b32 in 10 GEMM loops, on top of the handover variant
# baseline (speedup 1.0000x reference)
.LBB0_296:
	s_ashr_i32 s75, s74, 31
	s_lshl_b64 s[28:29], s[74:75], 20
	s_add_u32 s28, s44, s28
	s_addc_u32 s29, s45, s29
	s_and_b64 s[30:31], s[8:9], exec
	s_cselect_b32 s25, s29, s37
	s_cselect_b32 s33, s28, s36
	s_ashr_i32 s65, s64, 31
	s_lshl_b64 s[30:31], s[64:65], 20
	s_add_u32 s42, s26, s30
	s_addc_u32 s43, s27, s31
	s_and_b64 s[30:31], s[8:9], exec
	s_cselect_b32 s40, s43, s39
	s_cselect_b32 s50, s42, s38
	s_add_u32 s36, s36, 0x80080
	s_addc_u32 s37, s37, 0
	s_add_u32 s38, s38, 0x100
	v_mov_b64_e32 v[4:5], 0
	s_addc_u32 s39, s39, 0
	s_mov_b32 s55, -2
	v_mov_b64_e32 v[6:7], 0
	v_mov_b64_e32 v[8:9], 0
	v_mov_b64_e32 v[10:11], 0
	v_mov_b64_e32 v[20:21], 0
	s_waitcnt vmcnt(0)
	v_mov_b64_e32 v[22:23], 0
	v_mov_b64_e32 v[24:25], 0
	v_mov_b64_e32 v[26:27], 0
	v_mov_b64_e32 v[36:37], 0
	v_mov_b64_e32 v[38:39], 0
	v_mov_b64_e32 v[40:41], 0
	v_mov_b64_e32 v[42:43], 0
	v_mov_b64_e32 v[52:53], 0
	v_mov_b64_e32 v[54:55], 0
	v_mov_b64_e32 v[56:57], 0
	v_mov_b64_e32 v[58:59], 0
	v_mov_b64_e32 v[12:13], 0
	v_mov_b64_e32 v[14:15], 0
	v_mov_b64_e32 v[16:17], 0
	v_mov_b64_e32 v[18:19], 0
	v_mov_b64_e32 v[28:29], 0
	v_mov_b64_e32 v[30:31], 0
	v_mov_b64_e32 v[32:33], 0
	v_mov_b64_e32 v[34:35], 0
	v_mov_b64_e32 v[44:45], 0
	v_mov_b64_e32 v[46:47], 0
	v_mov_b64_e32 v[48:49], 0
	v_mov_b64_e32 v[50:51], 0
	v_mov_b64_e32 v[60:61], 0
	v_mov_b64_e32 v[62:63], 0
	v_mov_b64_e32 v[64:65], 0
	v_mov_b64_e32 v[66:67], 0
	v_mov_b64_e32 v[68:69], 0
	v_mov_b64_e32 v[70:71], 0
	v_mov_b64_e32 v[72:73], 0
	v_mov_b64_e32 v[74:75], 0
	v_mov_b64_e32 v[84:85], 0
	v_mov_b64_e32 v[86:87], 0
	v_mov_b64_e32 v[88:89], 0
	v_mov_b64_e32 v[90:91], 0
	v_mov_b64_e32 v[100:101], 0
	v_mov_b64_e32 v[102:103], 0
	v_mov_b64_e32 v[104:105], 0
	v_mov_b64_e32 v[106:107], 0
	v_mov_b64_e32 v[116:117], 0
	v_mov_b64_e32 v[118:119], 0
	v_mov_b64_e32 v[120:121], 0
	v_mov_b64_e32 v[122:123], 0
	v_mov_b64_e32 v[76:77], 0
	v_mov_b64_e32 v[78:79], 0
	v_mov_b64_e32 v[80:81], 0
	v_mov_b64_e32 v[82:83], 0
	v_mov_b64_e32 v[92:93], 0
	v_mov_b64_e32 v[94:95], 0
	v_mov_b64_e32 v[96:97], 0
	v_mov_b64_e32 v[98:99], 0
	v_mov_b64_e32 v[108:109], 0
	v_mov_b64_e32 v[110:111], 0
	v_mov_b64_e32 v[112:113], 0
	v_mov_b64_e32 v[114:115], 0
	v_mov_b64_e32 v[124:125], 0
	v_mov_b64_e32 v[126:127], 0
	v_mov_b64_e32 v[128:129], 0
	v_mov_b64_e32 v[130:131], 0

.LBB0_335:
	s_ashr_i32 s65, s64, 31
	s_lshl_b64 s[24:25], s[64:65], 20
	s_add_u32 s28, s52, s24
	s_addc_u32 s29, s53, s25
	s_and_b64 s[24:25], s[8:9], exec
	s_cselect_b32 s24, s29, s37
	s_cselect_b32 s25, s28, s36
	s_ashr_i32 s75, s74, 31
	s_lshl_b64 s[30:31], s[74:75], 20
	s_add_u32 s42, s26, s30
	s_addc_u32 s43, s27, s31
	s_and_b64 s[30:31], s[8:9], exec
	s_cselect_b32 s33, s43, s39
	s_cselect_b32 s40, s42, s38
	s_add_u32 s36, s36, 0x80080
	s_addc_u32 s37, s37, 0
	s_add_u32 s38, s38, 0x100
	v_mov_b64_e32 v[4:5], 0
	s_addc_u32 s39, s39, 0
	s_mov_b32 s50, -2
	v_mov_b64_e32 v[6:7], 0
	v_mov_b64_e32 v[8:9], 0
	v_mov_b64_e32 v[10:11], 0
	v_mov_b64_e32 v[20:21], 0
	s_waitcnt vmcnt(0)
	v_mov_b64_e32 v[22:23], 0
	v_mov_b64_e32 v[24:25], 0
	v_mov_b64_e32 v[26:27], 0
	v_mov_b64_e32 v[36:37], 0
	v_mov_b64_e32 v[38:39], 0
	v_mov_b64_e32 v[40:41], 0
	v_mov_b64_e32 v[42:43], 0
	v_mov_b64_e32 v[52:53], 0
	v_mov_b64_e32 v[54:55], 0
	v_mov_b64_e32 v[56:57], 0
	v_mov_b64_e32 v[58:59], 0
	v_mov_b64_e32 v[12:13], 0
	v_mov_b64_e32 v[14:15], 0
	v_mov_b64_e32 v[16:17], 0
	v_mov_b64_e32 v[18:19], 0
	v_mov_b64_e32 v[28:29], 0
	v_mov_b64_e32 v[30:31], 0
	v_mov_b64_e32 v[32:33], 0
	v_mov_b64_e32 v[34:35], 0
	v_mov_b64_e32 v[44:45], 0
	v_mov_b64_e32 v[46:47], 0
	v_mov_b64_e32 v[48:49], 0
	v_mov_b64_e32 v[50:51], 0
	v_mov_b64_e32 v[60:61], 0
	v_mov_b64_e32 v[62:63], 0
	v_mov_b64_e32 v[64:65], 0
	v_mov_b64_e32 v[66:67], 0
	v_mov_b64_e32 v[68:69], 0
	v_mov_b64_e32 v[70:71], 0
	v_mov_b64_e32 v[72:73], 0
	v_mov_b64_e32 v[74:75], 0
	v_mov_b64_e32 v[84:85], 0
	v_mov_b64_e32 v[86:87], 0
	v_mov_b64_e32 v[88:89], 0
	v_mov_b64_e32 v[90:91], 0
	v_mov_b64_e32 v[100:101], 0
	v_mov_b64_e32 v[102:103], 0
	v_mov_b64_e32 v[104:105], 0
	v_mov_b64_e32 v[106:107], 0
	v_mov_b64_e32 v[116:117], 0
	v_mov_b64_e32 v[118:119], 0
	v_mov_b64_e32 v[120:121], 0
	v_mov_b64_e32 v[122:123], 0
	v_mov_b64_e32 v[76:77], 0
	v_mov_b64_e32 v[78:79], 0
	v_mov_b64_e32 v[80:81], 0
	v_mov_b64_e32 v[82:83], 0
	v_mov_b64_e32 v[92:93], 0
	v_mov_b64_e32 v[94:95], 0
	v_mov_b64_e32 v[96:97], 0
	v_mov_b64_e32 v[98:99], 0
	v_mov_b64_e32 v[108:109], 0
	v_mov_b64_e32 v[110:111], 0
	v_mov_b64_e32 v[112:113], 0
	v_mov_b64_e32 v[114:115], 0
	v_mov_b64_e32 v[124:125], 0
	v_mov_b64_e32 v[126:127], 0
	v_mov_b64_e32 v[128:129], 0
	v_mov_b64_e32 v[130:131], 0

.LBB0_966:
	s_ashr_i32 s63, s62, 31
	s_lshl_b64 s[30:31], s[62:63], 20
	s_add_u32 s0, s27, s30
	s_addc_u32 s6, s46, s31
	s_and_b64 s[30:31], s[12:13], exec
	s_cselect_b32 s65, s6, s37
	s_cselect_b32 s64, s0, s36
	s_ashr_i32 s61, s60, 31
	s_lshl_b64 s[30:31], s[60:61], 20
	s_add_u32 s0, s47, s30
	s_addc_u32 s6, s59, s31
	s_and_b64 s[30:31], s[12:13], exec
	s_cselect_b32 s67, s6, s39
	s_cselect_b32 s66, s0, s38
	s_add_u32 s36, s36, 0x80080
	s_addc_u32 s37, s37, 0
	s_add_u32 s38, s38, 0x100
	v_mov_b64_e32 v[4:5], 0
	s_addc_u32 s39, s39, 0
	s_mov_b32 s55, -2
	v_mov_b64_e32 v[6:7], 0
	v_mov_b64_e32 v[8:9], 0
	v_mov_b64_e32 v[10:11], 0
	v_mov_b64_e32 v[20:21], 0
	s_waitcnt vmcnt(0)
	v_mov_b64_e32 v[22:23], 0
	v_mov_b64_e32 v[24:25], 0
	v_mov_b64_e32 v[26:27], 0
	v_mov_b64_e32 v[36:37], 0
	v_mov_b64_e32 v[38:39], 0
	v_mov_b64_e32 v[40:41], 0
	v_mov_b64_e32 v[42:43], 0
	v_mov_b64_e32 v[52:53], 0
	v_mov_b64_e32 v[54:55], 0
	v_mov_b64_e32 v[56:57], 0
	v_mov_b64_e32 v[58:59], 0
	v_mov_b64_e32 v[12:13], 0
	v_mov_b64_e32 v[14:15], 0
	v_mov_b64_e32 v[16:17], 0
	v_mov_b64_e32 v[18:19], 0
	v_mov_b64_e32 v[28:29], 0
	v_mov_b64_e32 v[30:31], 0
	v_mov_b64_e32 v[32:33], 0
	v_mov_b64_e32 v[34:35], 0
	v_mov_b64_e32 v[44:45], 0
	v_mov_b64_e32 v[46:47], 0
	v_mov_b64_e32 v[48:49], 0
	v_mov_b64_e32 v[50:51], 0
	v_mov_b64_e32 v[60:61], 0
	v_mov_b64_e32 v[62:63], 0
	v_mov_b64_e32 v[64:65], 0
	v_mov_b64_e32 v[66:67], 0
	v_mov_b64_e32 v[68:69], 0
	v_mov_b64_e32 v[70:71], 0
	v_mov_b64_e32 v[72:73], 0
	v_mov_b64_e32 v[74:75], 0
	v_mov_b64_e32 v[84:85], 0
	v_mov_b64_e32 v[86:87], 0
	v_mov_b64_e32 v[88:89], 0
	v_mov_b64_e32 v[90:91], 0
	v_mov_b64_e32 v[100:101], 0
	v_mov_b64_e32 v[102:103], 0
	v_mov_b64_e32 v[104:105], 0
	v_mov_b64_e32 v[106:107], 0
	v_mov_b64_e32 v[116:117], 0
	v_mov_b64_e32 v[118:119], 0
	v_mov_b64_e32 v[120:121], 0
	v_mov_b64_e32 v[122:123], 0
	v_mov_b64_e32 v[76:77], 0
	v_mov_b64_e32 v[78:79], 0
	v_mov_b64_e32 v[80:81], 0
	v_mov_b64_e32 v[82:83], 0
	v_mov_b64_e32 v[92:93], 0
	v_mov_b64_e32 v[94:95], 0
	v_mov_b64_e32 v[96:97], 0
	v_mov_b64_e32 v[98:99], 0
	v_mov_b64_e32 v[108:109], 0
	v_mov_b64_e32 v[110:111], 0
	v_mov_b64_e32 v[112:113], 0
	v_mov_b64_e32 v[114:115], 0
	v_mov_b64_e32 v[132:133], 0
	v_mov_b64_e32 v[134:135], 0
	v_mov_b64_e32 v[136:137], 0
	v_mov_b64_e32 v[138:139], 0

.LBB0_1016:
	v_mov_b64_e32 v[4:5], 0
	s_mov_b32 s30, 0
	s_mov_b64 s[80:81], -1
	s_mov_b64 s[36:37], 0
	s_waitcnt lgkmcnt(0)
	v_mov_b64_e32 v[6:7], 0
	v_mov_b64_e32 v[8:9], 0
	v_mov_b64_e32 v[10:11], 0
	v_mov_b64_e32 v[20:21], 0
	v_mov_b64_e32 v[22:23], 0
	v_mov_b64_e32 v[24:25], 0
	v_mov_b64_e32 v[26:27], 0
	v_mov_b64_e32 v[36:37], 0
	v_mov_b64_e32 v[38:39], 0
	v_mov_b64_e32 v[40:41], 0
	v_mov_b64_e32 v[42:43], 0
	v_mov_b64_e32 v[52:53], 0
	v_mov_b64_e32 v[54:55], 0
	v_mov_b64_e32 v[56:57], 0
	v_mov_b64_e32 v[58:59], 0
	v_mov_b64_e32 v[12:13], 0
	v_mov_b64_e32 v[14:15], 0
	v_mov_b64_e32 v[16:17], 0
	v_mov_b64_e32 v[18:19], 0
	v_mov_b64_e32 v[28:29], 0
	v_mov_b64_e32 v[30:31], 0
	v_mov_b64_e32 v[32:33], 0
	v_mov_b64_e32 v[34:35], 0
	v_mov_b64_e32 v[44:45], 0
	v_mov_b64_e32 v[46:47], 0
	v_mov_b64_e32 v[48:49], 0
	v_mov_b64_e32 v[50:51], 0
	v_mov_b64_e32 v[60:61], 0
	v_mov_b64_e32 v[62:63], 0
	v_mov_b64_e32 v[64:65], 0
	v_mov_b64_e32 v[66:67], 0
	v_mov_b64_e32 v[68:69], 0
	v_mov_b64_e32 v[70:71], 0
	v_mov_b64_e32 v[72:73], 0
	v_mov_b64_e32 v[74:75], 0
	v_mov_b64_e32 v[84:85], 0
	v_mov_b64_e32 v[86:87], 0
	v_mov_b64_e32 v[88:89], 0
	v_mov_b64_e32 v[90:91], 0
	v_mov_b64_e32 v[100:101], 0
	v_mov_b64_e32 v[102:103], 0
	v_mov_b64_e32 v[104:105], 0
	v_mov_b64_e32 v[106:107], 0
	v_mov_b64_e32 v[116:117], 0
	v_mov_b64_e32 v[118:119], 0
	v_mov_b64_e32 v[120:121], 0
	v_mov_b64_e32 v[122:123], 0
	v_mov_b64_e32 v[76:77], 0
	v_mov_b64_e32 v[78:79], 0
	v_mov_b64_e32 v[80:81], 0
	v_mov_b64_e32 v[82:83], 0
	v_mov_b64_e32 v[92:93], 0
	v_mov_b64_e32 v[94:95], 0
	v_mov_b64_e32 v[96:97], 0
	v_mov_b64_e32 v[98:99], 0
	v_mov_b64_e32 v[108:109], 0
	v_mov_b64_e32 v[110:111], 0
	v_mov_b64_e32 v[112:113], 0
	v_mov_b64_e32 v[114:115], 0
	v_mov_b64_e32 v[124:125], 0
	v_mov_b64_e32 v[126:127], 0
	v_mov_b64_e32 v[128:129], 0
	v_mov_b64_e32 v[130:131], 0

.LBB0_1136:
	s_ashr_i32 s29, s28, 31
	s_lshl_b64 s[30:31], s[28:29], 20
	s_add_u32 s42, s4, s30
	s_addc_u32 s43, s24, s31
	s_and_b64 s[30:31], s[10:11], exec
	s_cselect_b32 s29, s43, s37
	s_cselect_b32 s64, s42, s36
	s_ashr_i32 s23, s22, 31
	s_lshl_b64 s[30:31], s[22:23], 20
	s_add_u32 s44, s47, s30
	s_addc_u32 s45, s52, s31
	s_and_b64 s[30:31], s[10:11], exec
	s_cselect_b32 s23, s45, s39
	s_cselect_b32 s65, s44, s38
	s_add_u32 s36, s36, 0x80080
	s_addc_u32 s37, s37, 0
	s_add_u32 s38, s38, 0x100
	v_mov_b64_e32 v[4:5], 0
	s_addc_u32 s39, s39, 0
	s_mov_b32 s66, -2
	v_mov_b64_e32 v[6:7], 0
	v_mov_b64_e32 v[8:9], 0
	v_mov_b64_e32 v[10:11], 0
	v_mov_b64_e32 v[20:21], 0
	v_mov_b64_e32 v[22:23], 0
	v_mov_b64_e32 v[24:25], 0
	v_mov_b64_e32 v[26:27], 0
	v_mov_b64_e32 v[36:37], 0
	v_mov_b64_e32 v[38:39], 0
	v_mov_b64_e32 v[40:41], 0
	v_mov_b64_e32 v[42:43], 0
	v_mov_b64_e32 v[52:53], 0
	v_mov_b64_e32 v[54:55], 0
	v_mov_b64_e32 v[56:57], 0
	v_mov_b64_e32 v[58:59], 0
	v_mov_b64_e32 v[12:13], 0
	v_mov_b64_e32 v[14:15], 0
	v_mov_b64_e32 v[16:17], 0
	v_mov_b64_e32 v[18:19], 0
	v_mov_b64_e32 v[28:29], 0
	v_mov_b64_e32 v[30:31], 0
	v_mov_b64_e32 v[32:33], 0
	v_mov_b64_e32 v[34:35], 0
	v_mov_b64_e32 v[44:45], 0
	v_mov_b64_e32 v[46:47], 0
	v_mov_b64_e32 v[48:49], 0
	v_mov_b64_e32 v[50:51], 0
	v_mov_b64_e32 v[60:61], 0
	v_mov_b64_e32 v[62:63], 0
	v_mov_b64_e32 v[64:65], 0
	v_mov_b64_e32 v[66:67], 0
	v_mov_b64_e32 v[68:69], 0
	v_mov_b64_e32 v[70:71], 0
	v_mov_b64_e32 v[72:73], 0
	v_mov_b64_e32 v[74:75], 0
	v_mov_b64_e32 v[84:85], 0
	v_mov_b64_e32 v[86:87], 0
	v_mov_b64_e32 v[88:89], 0
	v_mov_b64_e32 v[90:91], 0
	v_mov_b64_e32 v[100:101], 0
	v_mov_b64_e32 v[102:103], 0
	v_mov_b64_e32 v[104:105], 0
	v_mov_b64_e32 v[106:107], 0
	v_mov_b64_e32 v[116:117], 0
	v_mov_b64_e32 v[118:119], 0
	v_mov_b64_e32 v[120:121], 0
	v_mov_b64_e32 v[122:123], 0
	v_mov_b64_e32 v[76:77], 0
	v_mov_b64_e32 v[78:79], 0
	v_mov_b64_e32 v[80:81], 0
	v_mov_b64_e32 v[82:83], 0
	v_mov_b64_e32 v[92:93], 0
	v_mov_b64_e32 v[94:95], 0
	v_mov_b64_e32 v[96:97], 0
	v_mov_b64_e32 v[98:99], 0
	v_mov_b64_e32 v[108:109], 0
	v_mov_b64_e32 v[110:111], 0
	v_mov_b64_e32 v[112:113], 0
	v_mov_b64_e32 v[114:115], 0
	v_mov_b64_e32 v[124:125], 0
	v_mov_b64_e32 v[126:127], 0
	v_mov_b64_e32 v[128:129], 0
	v_mov_b64_e32 v[130:131], 0

.LBB0_1166:
	s_ashr_i32 s43, s42, 31
	s_lshl_b64 s[30:31], s[42:43], 20
	s_add_u32 s44, s4, s30
	s_addc_u32 s45, s24, s31
	s_and_b64 s[30:31], s[22:23], exec
	s_cselect_b32 s43, s45, s37
	s_cselect_b32 s65, s44, s36
	s_ashr_i32 s29, s28, 31
	s_lshl_b64 s[30:31], s[28:29], 20
	s_add_u32 s60, s47, s30
	s_addc_u32 s61, s52, s31
	s_and_b64 s[30:31], s[22:23], exec
	s_cselect_b32 s29, s61, s39
	s_cselect_b32 s66, s60, s38
	s_add_u32 s36, s36, 0x80080
	s_addc_u32 s37, s37, 0
	s_add_u32 s38, s38, 0x100
	v_mov_b64_e32 v[4:5], 0
	s_addc_u32 s39, s39, 0
	s_mov_b32 s67, -2
	v_mov_b64_e32 v[6:7], 0
	v_mov_b64_e32 v[8:9], 0
	v_mov_b64_e32 v[10:11], 0
	v_mov_b64_e32 v[20:21], 0
	v_mov_b64_e32 v[22:23], 0
	v_mov_b64_e32 v[24:25], 0
	v_mov_b64_e32 v[26:27], 0
	v_mov_b64_e32 v[36:37], 0
	v_mov_b64_e32 v[38:39], 0
	v_mov_b64_e32 v[40:41], 0
	v_mov_b64_e32 v[42:43], 0
	v_mov_b64_e32 v[52:53], 0
	v_mov_b64_e32 v[54:55], 0
	v_mov_b64_e32 v[56:57], 0
	v_mov_b64_e32 v[58:59], 0
	v_mov_b64_e32 v[12:13], 0
	v_mov_b64_e32 v[14:15], 0
	v_mov_b64_e32 v[16:17], 0
	v_mov_b64_e32 v[18:19], 0
	v_mov_b64_e32 v[28:29], 0
	v_mov_b64_e32 v[30:31], 0
	v_mov_b64_e32 v[32:33], 0
	v_mov_b64_e32 v[34:35], 0
	v_mov_b64_e32 v[44:45], 0
	v_mov_b64_e32 v[46:47], 0
	v_mov_b64_e32 v[48:49], 0
	v_mov_b64_e32 v[50:51], 0
	v_mov_b64_e32 v[60:61], 0
	v_mov_b64_e32 v[62:63], 0
	v_mov_b64_e32 v[64:65], 0
	v_mov_b64_e32 v[66:67], 0
	v_mov_b64_e32 v[68:69], 0
	v_mov_b64_e32 v[70:71], 0
	v_mov_b64_e32 v[72:73], 0
	v_mov_b64_e32 v[74:75], 0
	v_mov_b64_e32 v[84:85], 0
	v_mov_b64_e32 v[86:87], 0
	v_mov_b64_e32 v[88:89], 0
	v_mov_b64_e32 v[90:91], 0
	v_mov_b64_e32 v[100:101], 0
	v_mov_b64_e32 v[102:103], 0
	v_mov_b64_e32 v[104:105], 0
	v_mov_b64_e32 v[106:107], 0
	v_mov_b64_e32 v[116:117], 0
	v_mov_b64_e32 v[118:119], 0
	v_mov_b64_e32 v[120:121], 0
	v_mov_b64_e32 v[122:123], 0
	v_mov_b64_e32 v[76:77], 0
	v_mov_b64_e32 v[78:79], 0
	v_mov_b64_e32 v[80:81], 0
	v_mov_b64_e32 v[82:83], 0
	v_mov_b64_e32 v[92:93], 0
	v_mov_b64_e32 v[94:95], 0
	v_mov_b64_e32 v[96:97], 0
	v_mov_b64_e32 v[98:99], 0
	v_mov_b64_e32 v[108:109], 0
	v_mov_b64_e32 v[110:111], 0
	v_mov_b64_e32 v[112:113], 0
	v_mov_b64_e32 v[114:115], 0
	v_mov_b64_e32 v[124:125], 0
	v_mov_b64_e32 v[126:127], 0
	v_mov_b64_e32 v[128:129], 0
	v_mov_b64_e32 v[130:131], 0

.LBB0_1185:
	s_ashr_i32 s29, s28, 31
	s_lshl_b64 s[30:31], s[28:29], 17
	s_add_u32 s42, s24, s30
	s_addc_u32 s43, s25, s31
	s_and_b64 s[30:31], s[10:11], exec
	s_cselect_b32 s29, s43, s65
	s_cselect_b32 s77, s42, s64
	s_ashr_i32 s23, s22, 31
	s_lshl_b64 s[30:31], s[22:23], 17
	s_add_u32 s44, s27, s30
	s_addc_u32 s45, s33, s31
	s_and_b64 s[30:31], s[10:11], exec
	v_mov_b64_e32 v[4:5], 0
	s_cselect_b32 s23, s45, s63
	s_cselect_b32 s78, s44, s62
	s_mov_b32 s30, 0
	s_mov_b64 s[66:67], -1
	s_mov_b64 s[36:37], 0
	v_mov_b64_e32 v[6:7], 0
	v_mov_b64_e32 v[8:9], 0
	v_mov_b64_e32 v[10:11], 0
	v_mov_b64_e32 v[12:13], 0
	v_mov_b64_e32 v[14:15], 0
	v_mov_b64_e32 v[20:21], 0
	v_mov_b64_e32 v[22:23], 0
	v_mov_b64_e32 v[28:29], 0
	v_mov_b64_e32 v[30:31], 0
	v_mov_b64_e32 v[36:37], 0
	v_mov_b64_e32 v[38:39], 0
	v_mov_b64_e32 v[44:45], 0
	v_mov_b64_e32 v[46:47], 0
	v_mov_b64_e32 v[52:53], 0
	v_mov_b64_e32 v[54:55], 0
	v_mov_b64_e32 v[16:17], 0
	v_mov_b64_e32 v[18:19], 0
	v_mov_b64_e32 v[24:25], 0
	v_mov_b64_e32 v[26:27], 0
	v_mov_b64_e32 v[32:33], 0
	v_mov_b64_e32 v[34:35], 0
	v_mov_b64_e32 v[40:41], 0
	v_mov_b64_e32 v[42:43], 0
	v_mov_b64_e32 v[48:49], 0
	v_mov_b64_e32 v[50:51], 0
	v_mov_b64_e32 v[56:57], 0
	v_mov_b64_e32 v[58:59], 0
	v_mov_b64_e32 v[60:61], 0
	v_mov_b64_e32 v[62:63], 0
	v_mov_b64_e32 v[64:65], 0
	v_mov_b64_e32 v[66:67], 0
	v_mov_b64_e32 v[68:69], 0
	v_mov_b64_e32 v[70:71], 0
	v_mov_b64_e32 v[72:73], 0
	v_mov_b64_e32 v[74:75], 0
	v_mov_b64_e32 v[76:77], 0
	v_mov_b64_e32 v[78:79], 0
	v_mov_b64_e32 v[84:85], 0
	v_mov_b64_e32 v[86:87], 0
	v_mov_b64_e32 v[92:93], 0
	v_mov_b64_e32 v[94:95], 0
	v_mov_b64_e32 v[100:101], 0
	v_mov_b64_e32 v[102:103], 0
	v_mov_b64_e32 v[108:109], 0
	v_mov_b64_e32 v[110:111], 0
	v_mov_b64_e32 v[116:117], 0
	v_mov_b64_e32 v[118:119], 0
	v_mov_b64_e32 v[80:81], 0
	v_mov_b64_e32 v[82:83], 0
	v_mov_b64_e32 v[88:89], 0
	v_mov_b64_e32 v[90:91], 0
	v_mov_b64_e32 v[96:97], 0
	v_mov_b64_e32 v[98:99], 0
	v_mov_b64_e32 v[104:105], 0
	v_mov_b64_e32 v[106:107], 0
	v_mov_b64_e32 v[112:113], 0
	v_mov_b64_e32 v[114:115], 0
	v_mov_b64_e32 v[120:121], 0
	v_mov_b64_e32 v[122:123], 0
	v_mov_b64_e32 v[124:125], 0
	v_mov_b64_e32 v[126:127], 0
	v_mov_b64_e32 v[128:129], 0
	v_mov_b64_e32 v[130:131], 0

.LBB0_1272:
	s_add_i32 s29, s61, -2
	s_add_u32 s69, s62, 0x100
	v_mov_b64_e32 v[4:5], 0
	s_addc_u32 s72, s63, 0
	s_mov_b32 s30, 0
	s_waitcnt lgkmcnt(0)
	v_mov_b64_e32 v[6:7], 0
	v_mov_b64_e32 v[8:9], 0
	v_mov_b64_e32 v[10:11], 0
	v_mov_b64_e32 v[20:21], 0
	v_mov_b64_e32 v[22:23], 0
	v_mov_b64_e32 v[24:25], 0
	v_mov_b64_e32 v[26:27], 0
	v_mov_b64_e32 v[36:37], 0
	v_mov_b64_e32 v[38:39], 0
	v_mov_b64_e32 v[40:41], 0
	v_mov_b64_e32 v[42:43], 0
	v_mov_b64_e32 v[52:53], 0
	v_mov_b64_e32 v[54:55], 0
	v_mov_b64_e32 v[56:57], 0
	v_mov_b64_e32 v[58:59], 0
	v_mov_b64_e32 v[12:13], 0
	v_mov_b64_e32 v[14:15], 0
	v_mov_b64_e32 v[16:17], 0
	v_mov_b64_e32 v[18:19], 0
	v_mov_b64_e32 v[28:29], 0
	v_mov_b64_e32 v[30:31], 0
	v_mov_b64_e32 v[32:33], 0
	v_mov_b64_e32 v[34:35], 0
	v_mov_b64_e32 v[44:45], 0
	v_mov_b64_e32 v[46:47], 0
	v_mov_b64_e32 v[48:49], 0
	v_mov_b64_e32 v[50:51], 0
	v_mov_b64_e32 v[60:61], 0
	v_mov_b64_e32 v[62:63], 0
	v_mov_b64_e32 v[64:65], 0
	v_mov_b64_e32 v[66:67], 0
	v_mov_b64_e32 v[68:69], 0
	v_mov_b64_e32 v[70:71], 0
	v_mov_b64_e32 v[72:73], 0
	v_mov_b64_e32 v[74:75], 0
	v_mov_b64_e32 v[84:85], 0
	v_mov_b64_e32 v[86:87], 0
	v_mov_b64_e32 v[88:89], 0
	v_mov_b64_e32 v[90:91], 0
	v_mov_b64_e32 v[100:101], 0
	v_mov_b64_e32 v[102:103], 0
	v_mov_b64_e32 v[104:105], 0
	v_mov_b64_e32 v[106:107], 0
	v_mov_b64_e32 v[116:117], 0
	v_mov_b64_e32 v[118:119], 0
	v_mov_b64_e32 v[120:121], 0
	v_mov_b64_e32 v[122:123], 0
	v_mov_b64_e32 v[76:77], 0
	v_mov_b64_e32 v[78:79], 0
	v_mov_b64_e32 v[80:81], 0
	v_mov_b64_e32 v[82:83], 0
	v_mov_b64_e32 v[92:93], 0
	v_mov_b64_e32 v[94:95], 0
	v_mov_b64_e32 v[96:97], 0
	v_mov_b64_e32 v[98:99], 0
	v_mov_b64_e32 v[108:109], 0
	v_mov_b64_e32 v[110:111], 0
	v_mov_b64_e32 v[112:113], 0
	v_mov_b64_e32 v[114:115], 0
	v_mov_b64_e32 v[132:133], 0
	v_mov_b64_e32 v[134:135], 0
	v_mov_b64_e32 v[136:137], 0
	v_mov_b64_e32 v[138:139], 0

.LBB0_1394:
	s_ashr_i32 s45, s44, 31
	s_lshl_b64 s[30:31], s[44:45], 20
	s_add_u32 s60, s12, s30
	s_addc_u32 s61, s13, s31
	s_and_b64 s[30:31], s[10:11], exec
	s_cselect_b32 s25, s61, s37
	s_cselect_b32 s33, s60, s36
	s_ashr_i32 s43, s42, 31
	s_lshl_b64 s[30:31], s[42:43], 20
	s_add_u32 s62, s27, s30
	s_addc_u32 s63, s51, s31
	s_and_b64 s[30:31], s[10:11], exec
	s_cselect_b32 s43, s63, s39
	s_cselect_b32 s45, s62, s38
	s_add_u32 s36, s36, 0x80080
	s_addc_u32 s37, s37, 0
	s_add_u32 s38, s38, 0x100
	v_mov_b64_e32 v[4:5], 0
	s_addc_u32 s39, s39, 0
	s_mov_b32 s67, -2
	v_mov_b64_e32 v[6:7], 0
	v_mov_b64_e32 v[8:9], 0
	v_mov_b64_e32 v[10:11], 0
	v_mov_b64_e32 v[20:21], 0
	v_mov_b64_e32 v[22:23], 0
	v_mov_b64_e32 v[24:25], 0
	v_mov_b64_e32 v[26:27], 0
	v_mov_b64_e32 v[36:37], 0
	v_mov_b64_e32 v[38:39], 0
	v_mov_b64_e32 v[40:41], 0
	v_mov_b64_e32 v[42:43], 0
	v_mov_b64_e32 v[52:53], 0
	v_mov_b64_e32 v[54:55], 0
	v_mov_b64_e32 v[56:57], 0
	v_mov_b64_e32 v[58:59], 0
	v_mov_b64_e32 v[12:13], 0
	v_mov_b64_e32 v[14:15], 0
	v_mov_b64_e32 v[16:17], 0
	v_mov_b64_e32 v[18:19], 0
	v_mov_b64_e32 v[28:29], 0
	v_mov_b64_e32 v[30:31], 0
	v_mov_b64_e32 v[32:33], 0
	v_mov_b64_e32 v[34:35], 0
	v_mov_b64_e32 v[44:45], 0
	v_mov_b64_e32 v[46:47], 0
	v_mov_b64_e32 v[48:49], 0
	v_mov_b64_e32 v[50:51], 0
	v_mov_b64_e32 v[60:61], 0
	v_mov_b64_e32 v[62:63], 0
	v_mov_b64_e32 v[64:65], 0
	v_mov_b64_e32 v[66:67], 0
	v_mov_b64_e32 v[68:69], 0
	v_mov_b64_e32 v[70:71], 0
	v_mov_b64_e32 v[72:73], 0
	v_mov_b64_e32 v[74:75], 0
	v_mov_b64_e32 v[84:85], 0
	v_mov_b64_e32 v[86:87], 0
	v_mov_b64_e32 v[88:89], 0
	v_mov_b64_e32 v[90:91], 0
	v_mov_b64_e32 v[100:101], 0
	v_mov_b64_e32 v[102:103], 0
	v_mov_b64_e32 v[104:105], 0
	v_mov_b64_e32 v[106:107], 0
	v_mov_b64_e32 v[116:117], 0
	v_mov_b64_e32 v[118:119], 0
	v_mov_b64_e32 v[120:121], 0
	v_mov_b64_e32 v[122:123], 0
	v_mov_b64_e32 v[76:77], 0
	v_mov_b64_e32 v[78:79], 0
	v_mov_b64_e32 v[80:81], 0
	v_mov_b64_e32 v[82:83], 0
	v_mov_b64_e32 v[92:93], 0
	v_mov_b64_e32 v[94:95], 0
	v_mov_b64_e32 v[96:97], 0
	v_mov_b64_e32 v[98:99], 0
	v_mov_b64_e32 v[108:109], 0
	v_mov_b64_e32 v[110:111], 0
	v_mov_b64_e32 v[112:113], 0
	v_mov_b64_e32 v[114:115], 0
	v_mov_b64_e32 v[124:125], 0
	v_mov_b64_e32 v[126:127], 0
	v_mov_b64_e32 v[128:129], 0
	v_mov_b64_e32 v[130:131], 0

.LBB0_1440:
	s_ashr_i32 s43, s42, 31
	s_lshl_b64 s[30:31], s[42:43], 20
	s_add_u32 s0, s12, s30
	s_addc_u32 s6, s13, s31
	s_ashr_i32 s75, s74, 31
	s_lshl_b64 s[30:31], s[74:75], 1
	s_add_u32 s76, s0, s30
	s_addc_u32 s77, s6, s31
	s_and_b64 s[34:35], s[60:61], exec
	s_cselect_b32 s43, s77, s63
	s_cselect_b32 s75, s76, s62
	s_ashr_i32 s45, s44, 31
	s_lshl_b64 s[34:35], s[44:45], 20
	s_add_u32 s0, s27, s34
	s_addc_u32 s6, s51, s35
	s_add_u32 s68, s0, s30
	s_addc_u32 s69, s6, s31
	s_and_b64 s[30:31], s[60:61], exec
	v_mov_b64_e32 v[4:5], 0
	s_cselect_b32 s45, s69, s67
	s_cselect_b32 s81, s68, s66
	s_mov_b32 s30, 0
	s_mov_b64 s[36:37], -1
	s_mov_b64 s[38:39], 0
	s_waitcnt lgkmcnt(0)
	v_mov_b64_e32 v[6:7], 0
	v_mov_b64_e32 v[8:9], 0
	v_mov_b64_e32 v[10:11], 0
	v_mov_b64_e32 v[20:21], 0
	v_mov_b64_e32 v[22:23], 0
	v_mov_b64_e32 v[24:25], 0
	v_mov_b64_e32 v[26:27], 0
	v_mov_b64_e32 v[36:37], 0
	v_mov_b64_e32 v[38:39], 0
	v_mov_b64_e32 v[40:41], 0
	v_mov_b64_e32 v[42:43], 0
	v_mov_b64_e32 v[52:53], 0
	v_mov_b64_e32 v[54:55], 0
	v_mov_b64_e32 v[56:57], 0
	v_mov_b64_e32 v[58:59], 0
	v_mov_b64_e32 v[12:13], 0
	v_mov_b64_e32 v[14:15], 0
	v_mov_b64_e32 v[16:17], 0
	v_mov_b64_e32 v[18:19], 0
	v_mov_b64_e32 v[28:29], 0
	v_mov_b64_e32 v[30:31], 0
	v_mov_b64_e32 v[32:33], 0
	v_mov_b64_e32 v[34:35], 0
	v_mov_b64_e32 v[44:45], 0
	v_mov_b64_e32 v[46:47], 0
	v_mov_b64_e32 v[48:49], 0
	v_mov_b64_e32 v[50:51], 0
	v_mov_b64_e32 v[60:61], 0
	v_mov_b64_e32 v[62:63], 0
	v_mov_b64_e32 v[64:65], 0
	v_mov_b64_e32 v[66:67], 0
	v_mov_b64_e32 v[68:69], 0
	v_mov_b64_e32 v[70:71], 0
	v_mov_b64_e32 v[72:73], 0
	v_mov_b64_e32 v[74:75], 0
	v_mov_b64_e32 v[84:85], 0
	v_mov_b64_e32 v[86:87], 0
	v_mov_b64_e32 v[88:89], 0
	v_mov_b64_e32 v[90:91], 0
	v_mov_b64_e32 v[100:101], 0
	v_mov_b64_e32 v[102:103], 0
	v_mov_b64_e32 v[104:105], 0
	v_mov_b64_e32 v[106:107], 0
	v_mov_b64_e32 v[116:117], 0
	v_mov_b64_e32 v[118:119], 0
	v_mov_b64_e32 v[120:121], 0
	v_mov_b64_e32 v[122:123], 0
	v_mov_b64_e32 v[76:77], 0
	v_mov_b64_e32 v[78:79], 0
	v_mov_b64_e32 v[80:81], 0
	v_mov_b64_e32 v[82:83], 0
	v_mov_b64_e32 v[92:93], 0
	v_mov_b64_e32 v[94:95], 0
	v_mov_b64_e32 v[96:97], 0
	v_mov_b64_e32 v[98:99], 0
	v_mov_b64_e32 v[108:109], 0
	v_mov_b64_e32 v[110:111], 0
	v_mov_b64_e32 v[112:113], 0
	v_mov_b64_e32 v[114:115], 0
	v_mov_b64_e32 v[124:125], 0
	v_mov_b64_e32 v[126:127], 0
	v_mov_b64_e32 v[128:129], 0
	v_mov_b64_e32 v[130:131], 0
